# adaLN modulation mat-vec with 16-byte weight loads (rows split over lane groups, fixed-order LDS reduction)
# baseline (speedup 1.0000x reference)
.LBB0_60:
	v_and_b32_e32 v64, 63, v186
	v_lshrrev_b32_e32 v65, 4, v64
	v_and_b32_e32 v66, 15, v64
	v_lshlrev_b32_e32 v67, 2, v64
	v_mov_b32_e32 v68, 0
	v_sub_co_u32_e32 v76, vcc, v20, v67
	s_nop 1
	v_subb_co_u32_e32 v77, vcc, v21, v68, vcc
	v_mul_u32_u24_e32 v72, 0x6000, v65
	v_lshl_add_u32 v72, v66, 4, v72
	v_mov_b32_e32 v73, 0
	v_lshl_add_u64 v[76:77], v[76:77], 0, v[72:73]
	s_mov_b64 s[0:1], 0x18000
	v_lshl_add_u32 v69, v65, 2, v38
	v_mov_b32_e32 v144, 0
	v_mov_b32_e32 v145, 0
	v_mov_b32_e32 v146, 0
	v_mov_b32_e32 v147, 0
	v_mov_b32_e32 v148, 0
	v_mov_b32_e32 v149, 0
	v_mov_b32_e32 v150, 0
	v_mov_b32_e32 v151, 0
	v_mov_b32_e32 v152, 0
	v_mov_b32_e32 v153, 0
	v_mov_b32_e32 v154, 0
	v_mov_b32_e32 v155, 0
	v_mov_b32_e32 v156, 0
	v_mov_b32_e32 v157, 0
	v_mov_b32_e32 v158, 0
	v_mov_b32_e32 v159, 0
	v_mov_b32_e32 v160, 0
	v_mov_b32_e32 v161, 0
	v_mov_b32_e32 v162, 0
	v_mov_b32_e32 v163, 0
	global_load_dwordx4 v[80:83], v[76:77], off
	v_lshl_add_u64 v[76:77], v[76:77], 0, s[0:1]
	global_load_dwordx4 v[84:87], v[76:77], off
	v_lshl_add_u64 v[76:77], v[76:77], 0, s[0:1]
	global_load_dwordx4 v[88:91], v[76:77], off
	v_lshl_add_u64 v[76:77], v[76:77], 0, s[0:1]
	global_load_dwordx4 v[92:95], v[76:77], off
	v_lshl_add_u64 v[76:77], v[76:77], 0, s[0:1]
	global_load_dwordx4 v[96:99], v[76:77], off
	v_lshl_add_u64 v[76:77], v[76:77], 0, s[0:1]
	global_load_dwordx4 v[100:103], v[76:77], off
	v_lshl_add_u64 v[76:77], v[76:77], 0, s[0:1]
	global_load_dwordx4 v[104:107], v[76:77], off
	v_lshl_add_u64 v[76:77], v[76:77], 0, s[0:1]
	global_load_dwordx4 v[108:111], v[76:77], off
	v_lshl_add_u64 v[76:77], v[76:77], 0, s[0:1]
	global_load_dwordx4 v[112:115], v[76:77], off
	v_lshl_add_u64 v[76:77], v[76:77], 0, s[0:1]
	global_load_dwordx4 v[116:119], v[76:77], off
	v_lshl_add_u64 v[76:77], v[76:77], 0, s[0:1]
	global_load_dwordx4 v[120:123], v[76:77], off
	v_lshl_add_u64 v[76:77], v[76:77], 0, s[0:1]
	global_load_dwordx4 v[124:127], v[76:77], off
	v_lshl_add_u64 v[76:77], v[76:77], 0, s[0:1]
	global_load_dwordx4 v[128:131], v[76:77], off
	v_lshl_add_u64 v[76:77], v[76:77], 0, s[0:1]
	global_load_dwordx4 v[132:135], v[76:77], off
	v_lshl_add_u64 v[76:77], v[76:77], 0, s[0:1]
	global_load_dwordx4 v[136:139], v[76:77], off
	v_lshl_add_u64 v[76:77], v[76:77], 0, s[0:1]
	global_load_dwordx4 v[140:143], v[76:77], off
	v_lshl_add_u64 v[76:77], v[76:77], 0, s[0:1]
	ds_read_b32 v44, v69 offset:0
	ds_read_b32 v45, v69 offset:4096
	ds_read_b32 v46, v69 offset:8192
	ds_read_b32 v47, v69 offset:12288
	ds_read_b32 v48, v69 offset:16384
	s_waitcnt vmcnt(15)
	s_waitcnt lgkmcnt(0)
	v_fmac_f32_e32 v144, v80, v44
	v_fmac_f32_e32 v145, v81, v44
	v_fmac_f32_e32 v146, v82, v44
	v_fmac_f32_e32 v147, v83, v44
	v_fmac_f32_e32 v148, v80, v45
	v_fmac_f32_e32 v149, v81, v45
	v_fmac_f32_e32 v150, v82, v45
	v_fmac_f32_e32 v151, v83, v45
	v_fmac_f32_e32 v152, v80, v46
	v_fmac_f32_e32 v153, v81, v46
	v_fmac_f32_e32 v154, v82, v46
	v_fmac_f32_e32 v155, v83, v46
	v_fmac_f32_e32 v156, v80, v47
	v_fmac_f32_e32 v157, v81, v47
	v_fmac_f32_e32 v158, v82, v47
	v_fmac_f32_e32 v159, v83, v47
	v_fmac_f32_e32 v160, v80, v48
	v_fmac_f32_e32 v161, v81, v48
	v_fmac_f32_e32 v162, v82, v48
	v_fmac_f32_e32 v163, v83, v48
	global_load_dwordx4 v[80:83], v[76:77], off
	v_lshl_add_u64 v[76:77], v[76:77], 0, s[0:1]
	ds_read_b32 v44, v69 offset:16
	ds_read_b32 v45, v69 offset:4112
	ds_read_b32 v46, v69 offset:8208
	ds_read_b32 v47, v69 offset:12304
	ds_read_b32 v48, v69 offset:16400
	s_waitcnt vmcnt(15)
	s_waitcnt lgkmcnt(0)
	v_fmac_f32_e32 v144, v84, v44
	v_fmac_f32_e32 v145, v85, v44
	v_fmac_f32_e32 v146, v86, v44
	v_fmac_f32_e32 v147, v87, v44
	v_fmac_f32_e32 v148, v84, v45
	v_fmac_f32_e32 v149, v85, v45
	v_fmac_f32_e32 v150, v86, v45
	v_fmac_f32_e32 v151, v87, v45
	v_fmac_f32_e32 v152, v84, v46
	v_fmac_f32_e32 v153, v85, v46
	v_fmac_f32_e32 v154, v86, v46
	v_fmac_f32_e32 v155, v87, v46
	v_fmac_f32_e32 v156, v84, v47
	v_fmac_f32_e32 v157, v85, v47
	v_fmac_f32_e32 v158, v86, v47
	v_fmac_f32_e32 v159, v87, v47
	v_fmac_f32_e32 v160, v84, v48
	v_fmac_f32_e32 v161, v85, v48
	v_fmac_f32_e32 v162, v86, v48
	v_fmac_f32_e32 v163, v87, v48
	global_load_dwordx4 v[84:87], v[76:77], off
	v_lshl_add_u64 v[76:77], v[76:77], 0, s[0:1]
	ds_read_b32 v44, v69 offset:32
	ds_read_b32 v45, v69 offset:4128
	ds_read_b32 v46, v69 offset:8224
	ds_read_b32 v47, v69 offset:12320
	ds_read_b32 v48, v69 offset:16416
	s_waitcnt vmcnt(15)
	s_waitcnt lgkmcnt(0)
	v_fmac_f32_e32 v144, v88, v44
	v_fmac_f32_e32 v145, v89, v44
	v_fmac_f32_e32 v146, v90, v44
	v_fmac_f32_e32 v147, v91, v44
	v_fmac_f32_e32 v148, v88, v45
	v_fmac_f32_e32 v149, v89, v45
	v_fmac_f32_e32 v150, v90, v45
	v_fmac_f32_e32 v151, v91, v45
	v_fmac_f32_e32 v152, v88, v46
	v_fmac_f32_e32 v153, v89, v46
	v_fmac_f32_e32 v154, v90, v46
	v_fmac_f32_e32 v155, v91, v46
	v_fmac_f32_e32 v156, v88, v47
	v_fmac_f32_e32 v157, v89, v47
	v_fmac_f32_e32 v158, v90, v47
	v_fmac_f32_e32 v159, v91, v47
	v_fmac_f32_e32 v160, v88, v48
	v_fmac_f32_e32 v161, v89, v48
	v_fmac_f32_e32 v162, v90, v48
	v_fmac_f32_e32 v163, v91, v48
	global_load_dwordx4 v[88:91], v[76:77], off
	v_lshl_add_u64 v[76:77], v[76:77], 0, s[0:1]
	ds_read_b32 v44, v69 offset:48
	ds_read_b32 v45, v69 offset:4144
	ds_read_b32 v46, v69 offset:8240
	ds_read_b32 v47, v69 offset:12336
	ds_read_b32 v48, v69 offset:16432
	s_waitcnt vmcnt(15)
	s_waitcnt lgkmcnt(0)
	v_fmac_f32_e32 v144, v92, v44
	v_fmac_f32_e32 v145, v93, v44
	v_fmac_f32_e32 v146, v94, v44
	v_fmac_f32_e32 v147, v95, v44
	v_fmac_f32_e32 v148, v92, v45
	v_fmac_f32_e32 v149, v93, v45
	v_fmac_f32_e32 v150, v94, v45
	v_fmac_f32_e32 v151, v95, v45
	v_fmac_f32_e32 v152, v92, v46
	v_fmac_f32_e32 v153, v93, v46
	v_fmac_f32_e32 v154, v94, v46
	v_fmac_f32_e32 v155, v95, v46
	v_fmac_f32_e32 v156, v92, v47
	v_fmac_f32_e32 v157, v93, v47
	v_fmac_f32_e32 v158, v94, v47
	v_fmac_f32_e32 v159, v95, v47
	v_fmac_f32_e32 v160, v92, v48
	v_fmac_f32_e32 v161, v93, v48
	v_fmac_f32_e32 v162, v94, v48
	v_fmac_f32_e32 v163, v95, v48
	global_load_dwordx4 v[92:95], v[76:77], off
	v_lshl_add_u64 v[76:77], v[76:77], 0, s[0:1]
	ds_read_b32 v44, v69 offset:64
	ds_read_b32 v45, v69 offset:4160
	ds_read_b32 v46, v69 offset:8256
	ds_read_b32 v47, v69 offset:12352
	ds_read_b32 v48, v69 offset:16448
	s_waitcnt vmcnt(15)
	s_waitcnt lgkmcnt(0)
	v_fmac_f32_e32 v144, v96, v44
	v_fmac_f32_e32 v145, v97, v44
	v_fmac_f32_e32 v146, v98, v44
	v_fmac_f32_e32 v147, v99, v44
	v_fmac_f32_e32 v148, v96, v45
	v_fmac_f32_e32 v149, v97, v45
	v_fmac_f32_e32 v150, v98, v45
	v_fmac_f32_e32 v151, v99, v45
	v_fmac_f32_e32 v152, v96, v46
	v_fmac_f32_e32 v153, v97, v46
	v_fmac_f32_e32 v154, v98, v46
	v_fmac_f32_e32 v155, v99, v46
	v_fmac_f32_e32 v156, v96, v47
	v_fmac_f32_e32 v157, v97, v47
	v_fmac_f32_e32 v158, v98, v47
	v_fmac_f32_e32 v159, v99, v47
	v_fmac_f32_e32 v160, v96, v48
	v_fmac_f32_e32 v161, v97, v48
	v_fmac_f32_e32 v162, v98, v48
	v_fmac_f32_e32 v163, v99, v48
	global_load_dwordx4 v[96:99], v[76:77], off
	v_lshl_add_u64 v[76:77], v[76:77], 0, s[0:1]
	ds_read_b32 v44, v69 offset:80
	ds_read_b32 v45, v69 offset:4176
	ds_read_b32 v46, v69 offset:8272
	ds_read_b32 v47, v69 offset:12368
	ds_read_b32 v48, v69 offset:16464
	s_waitcnt vmcnt(15)
	s_waitcnt lgkmcnt(0)
	v_fmac_f32_e32 v144, v100, v44
	v_fmac_f32_e32 v145, v101, v44
	v_fmac_f32_e32 v146, v102, v44
	v_fmac_f32_e32 v147, v103, v44
	v_fmac_f32_e32 v148, v100, v45
	v_fmac_f32_e32 v149, v101, v45
	v_fmac_f32_e32 v150, v102, v45
	v_fmac_f32_e32 v151, v103, v45
	v_fmac_f32_e32 v152, v100, v46
	v_fmac_f32_e32 v153, v101, v46
	v_fmac_f32_e32 v154, v102, v46
	v_fmac_f32_e32 v155, v103, v46
	v_fmac_f32_e32 v156, v100, v47
	v_fmac_f32_e32 v157, v101, v47
	v_fmac_f32_e32 v158, v102, v47
	v_fmac_f32_e32 v159, v103, v47
	v_fmac_f32_e32 v160, v100, v48
	v_fmac_f32_e32 v161, v101, v48
	v_fmac_f32_e32 v162, v102, v48
	v_fmac_f32_e32 v163, v103, v48
	global_load_dwordx4 v[100:103], v[76:77], off
	v_lshl_add_u64 v[76:77], v[76:77], 0, s[0:1]
	ds_read_b32 v44, v69 offset:96
	ds_read_b32 v45, v69 offset:4192
	ds_read_b32 v46, v69 offset:8288
	ds_read_b32 v47, v69 offset:12384
	ds_read_b32 v48, v69 offset:16480
	s_waitcnt vmcnt(15)
	s_waitcnt lgkmcnt(0)
	v_fmac_f32_e32 v144, v104, v44
	v_fmac_f32_e32 v145, v105, v44
	v_fmac_f32_e32 v146, v106, v44
	v_fmac_f32_e32 v147, v107, v44
	v_fmac_f32_e32 v148, v104, v45
	v_fmac_f32_e32 v149, v105, v45
	v_fmac_f32_e32 v150, v106, v45
	v_fmac_f32_e32 v151, v107, v45
	v_fmac_f32_e32 v152, v104, v46
	v_fmac_f32_e32 v153, v105, v46
	v_fmac_f32_e32 v154, v106, v46
	v_fmac_f32_e32 v155, v107, v46
	v_fmac_f32_e32 v156, v104, v47
	v_fmac_f32_e32 v157, v105, v47
	v_fmac_f32_e32 v158, v106, v47
	v_fmac_f32_e32 v159, v107, v47
	v_fmac_f32_e32 v160, v104, v48
	v_fmac_f32_e32 v161, v105, v48
	v_fmac_f32_e32 v162, v106, v48
	v_fmac_f32_e32 v163, v107, v48
	global_load_dwordx4 v[104:107], v[76:77], off
	v_lshl_add_u64 v[76:77], v[76:77], 0, s[0:1]
	ds_read_b32 v44, v69 offset:112
	ds_read_b32 v45, v69 offset:4208
	ds_read_b32 v46, v69 offset:8304
	ds_read_b32 v47, v69 offset:12400
	ds_read_b32 v48, v69 offset:16496
	s_waitcnt vmcnt(15)
	s_waitcnt lgkmcnt(0)
	v_fmac_f32_e32 v144, v108, v44
	v_fmac_f32_e32 v145, v109, v44
	v_fmac_f32_e32 v146, v110, v44
	v_fmac_f32_e32 v147, v111, v44
	v_fmac_f32_e32 v148, v108, v45
	v_fmac_f32_e32 v149, v109, v45
	v_fmac_f32_e32 v150, v110, v45
	v_fmac_f32_e32 v151, v111, v45
	v_fmac_f32_e32 v152, v108, v46
	v_fmac_f32_e32 v153, v109, v46
	v_fmac_f32_e32 v154, v110, v46
	v_fmac_f32_e32 v155, v111, v46
	v_fmac_f32_e32 v156, v108, v47
	v_fmac_f32_e32 v157, v109, v47
	v_fmac_f32_e32 v158, v110, v47
	v_fmac_f32_e32 v159, v111, v47
	v_fmac_f32_e32 v160, v108, v48
	v_fmac_f32_e32 v161, v109, v48
	v_fmac_f32_e32 v162, v110, v48
	v_fmac_f32_e32 v163, v111, v48
	global_load_dwordx4 v[108:111], v[76:77], off
	v_lshl_add_u64 v[76:77], v[76:77], 0, s[0:1]
	ds_read_b32 v44, v69 offset:128
	ds_read_b32 v45, v69 offset:4224
	ds_read_b32 v46, v69 offset:8320
	ds_read_b32 v47, v69 offset:12416
	ds_read_b32 v48, v69 offset:16512
	s_waitcnt vmcnt(15)
	s_waitcnt lgkmcnt(0)
	v_fmac_f32_e32 v144, v112, v44
	v_fmac_f32_e32 v145, v113, v44
	v_fmac_f32_e32 v146, v114, v44
	v_fmac_f32_e32 v147, v115, v44
	v_fmac_f32_e32 v148, v112, v45
	v_fmac_f32_e32 v149, v113, v45
	v_fmac_f32_e32 v150, v114, v45
	v_fmac_f32_e32 v151, v115, v45
	v_fmac_f32_e32 v152, v112, v46
	v_fmac_f32_e32 v153, v113, v46
	v_fmac_f32_e32 v154, v114, v46
	v_fmac_f32_e32 v155, v115, v46
	v_fmac_f32_e32 v156, v112, v47
	v_fmac_f32_e32 v157, v113, v47
	v_fmac_f32_e32 v158, v114, v47
	v_fmac_f32_e32 v159, v115, v47
	v_fmac_f32_e32 v160, v112, v48
	v_fmac_f32_e32 v161, v113, v48
	v_fmac_f32_e32 v162, v114, v48
	v_fmac_f32_e32 v163, v115, v48
	global_load_dwordx4 v[112:115], v[76:77], off
	v_lshl_add_u64 v[76:77], v[76:77], 0, s[0:1]
	ds_read_b32 v44, v69 offset:144
	ds_read_b32 v45, v69 offset:4240
	ds_read_b32 v46, v69 offset:8336
	ds_read_b32 v47, v69 offset:12432
	ds_read_b32 v48, v69 offset:16528
	s_waitcnt vmcnt(15)
	s_waitcnt lgkmcnt(0)
	v_fmac_f32_e32 v144, v116, v44
	v_fmac_f32_e32 v145, v117, v44
	v_fmac_f32_e32 v146, v118, v44
	v_fmac_f32_e32 v147, v119, v44
	v_fmac_f32_e32 v148, v116, v45
	v_fmac_f32_e32 v149, v117, v45
	v_fmac_f32_e32 v150, v118, v45
	v_fmac_f32_e32 v151, v119, v45
	v_fmac_f32_e32 v152, v116, v46
	v_fmac_f32_e32 v153, v117, v46
	v_fmac_f32_e32 v154, v118, v46
	v_fmac_f32_e32 v155, v119, v46
	v_fmac_f32_e32 v156, v116, v47
	v_fmac_f32_e32 v157, v117, v47
	v_fmac_f32_e32 v158, v118, v47
	v_fmac_f32_e32 v159, v119, v47
	v_fmac_f32_e32 v160, v116, v48
	v_fmac_f32_e32 v161, v117, v48
	v_fmac_f32_e32 v162, v118, v48
	v_fmac_f32_e32 v163, v119, v48
	global_load_dwordx4 v[116:119], v[76:77], off
	v_lshl_add_u64 v[76:77], v[76:77], 0, s[0:1]
	ds_read_b32 v44, v69 offset:160
	ds_read_b32 v45, v69 offset:4256
	ds_read_b32 v46, v69 offset:8352
	ds_read_b32 v47, v69 offset:12448
	ds_read_b32 v48, v69 offset:16544
	s_waitcnt vmcnt(15)
	s_waitcnt lgkmcnt(0)
	v_fmac_f32_e32 v144, v120, v44
	v_fmac_f32_e32 v145, v121, v44
	v_fmac_f32_e32 v146, v122, v44
	v_fmac_f32_e32 v147, v123, v44
	v_fmac_f32_e32 v148, v120, v45
	v_fmac_f32_e32 v149, v121, v45
	v_fmac_f32_e32 v150, v122, v45
	v_fmac_f32_e32 v151, v123, v45
	v_fmac_f32_e32 v152, v120, v46
	v_fmac_f32_e32 v153, v121, v46
	v_fmac_f32_e32 v154, v122, v46
	v_fmac_f32_e32 v155, v123, v46
	v_fmac_f32_e32 v156, v120, v47
	v_fmac_f32_e32 v157, v121, v47
	v_fmac_f32_e32 v158, v122, v47
	v_fmac_f32_e32 v159, v123, v47
	v_fmac_f32_e32 v160, v120, v48
	v_fmac_f32_e32 v161, v121, v48
	v_fmac_f32_e32 v162, v122, v48
	v_fmac_f32_e32 v163, v123, v48
	global_load_dwordx4 v[120:123], v[76:77], off
	v_lshl_add_u64 v[76:77], v[76:77], 0, s[0:1]
	ds_read_b32 v44, v69 offset:176
	ds_read_b32 v45, v69 offset:4272
	ds_read_b32 v46, v69 offset:8368
	ds_read_b32 v47, v69 offset:12464
	ds_read_b32 v48, v69 offset:16560
	s_waitcnt vmcnt(15)
	s_waitcnt lgkmcnt(0)
	v_fmac_f32_e32 v144, v124, v44
	v_fmac_f32_e32 v145, v125, v44
	v_fmac_f32_e32 v146, v126, v44
	v_fmac_f32_e32 v147, v127, v44
	v_fmac_f32_e32 v148, v124, v45
	v_fmac_f32_e32 v149, v125, v45
	v_fmac_f32_e32 v150, v126, v45
	v_fmac_f32_e32 v151, v127, v45
	v_fmac_f32_e32 v152, v124, v46
	v_fmac_f32_e32 v153, v125, v46
	v_fmac_f32_e32 v154, v126, v46
	v_fmac_f32_e32 v155, v127, v46
	v_fmac_f32_e32 v156, v124, v47
	v_fmac_f32_e32 v157, v125, v47
	v_fmac_f32_e32 v158, v126, v47
	v_fmac_f32_e32 v159, v127, v47
	v_fmac_f32_e32 v160, v124, v48
	v_fmac_f32_e32 v161, v125, v48
	v_fmac_f32_e32 v162, v126, v48
	v_fmac_f32_e32 v163, v127, v48
	global_load_dwordx4 v[124:127], v[76:77], off
	v_lshl_add_u64 v[76:77], v[76:77], 0, s[0:1]
	ds_read_b32 v44, v69 offset:192
	ds_read_b32 v45, v69 offset:4288
	ds_read_b32 v46, v69 offset:8384
	ds_read_b32 v47, v69 offset:12480
	ds_read_b32 v48, v69 offset:16576
	s_waitcnt vmcnt(15)
	s_waitcnt lgkmcnt(0)
	v_fmac_f32_e32 v144, v128, v44
	v_fmac_f32_e32 v145, v129, v44
	v_fmac_f32_e32 v146, v130, v44
	v_fmac_f32_e32 v147, v131, v44
	v_fmac_f32_e32 v148, v128, v45
	v_fmac_f32_e32 v149, v129, v45
	v_fmac_f32_e32 v150, v130, v45
	v_fmac_f32_e32 v151, v131, v45
	v_fmac_f32_e32 v152, v128, v46
	v_fmac_f32_e32 v153, v129, v46
	v_fmac_f32_e32 v154, v130, v46
	v_fmac_f32_e32 v155, v131, v46
	v_fmac_f32_e32 v156, v128, v47
	v_fmac_f32_e32 v157, v129, v47
	v_fmac_f32_e32 v158, v130, v47
	v_fmac_f32_e32 v159, v131, v47
	v_fmac_f32_e32 v160, v128, v48
	v_fmac_f32_e32 v161, v129, v48
	v_fmac_f32_e32 v162, v130, v48
	v_fmac_f32_e32 v163, v131, v48
	global_load_dwordx4 v[128:131], v[76:77], off
	v_lshl_add_u64 v[76:77], v[76:77], 0, s[0:1]
	ds_read_b32 v44, v69 offset:208
	ds_read_b32 v45, v69 offset:4304
	ds_read_b32 v46, v69 offset:8400
	ds_read_b32 v47, v69 offset:12496
	ds_read_b32 v48, v69 offset:16592
	s_waitcnt vmcnt(15)
	s_waitcnt lgkmcnt(0)
	v_fmac_f32_e32 v144, v132, v44
	v_fmac_f32_e32 v145, v133, v44
	v_fmac_f32_e32 v146, v134, v44
	v_fmac_f32_e32 v147, v135, v44
	v_fmac_f32_e32 v148, v132, v45
	v_fmac_f32_e32 v149, v133, v45
	v_fmac_f32_e32 v150, v134, v45
	v_fmac_f32_e32 v151, v135, v45
	v_fmac_f32_e32 v152, v132, v46
	v_fmac_f32_e32 v153, v133, v46
	v_fmac_f32_e32 v154, v134, v46
	v_fmac_f32_e32 v155, v135, v46
	v_fmac_f32_e32 v156, v132, v47
	v_fmac_f32_e32 v157, v133, v47
	v_fmac_f32_e32 v158, v134, v47
	v_fmac_f32_e32 v159, v135, v47
	v_fmac_f32_e32 v160, v132, v48
	v_fmac_f32_e32 v161, v133, v48
	v_fmac_f32_e32 v162, v134, v48
	v_fmac_f32_e32 v163, v135, v48
	global_load_dwordx4 v[132:135], v[76:77], off
	v_lshl_add_u64 v[76:77], v[76:77], 0, s[0:1]
	ds_read_b32 v44, v69 offset:224
	ds_read_b32 v45, v69 offset:4320
	ds_read_b32 v46, v69 offset:8416
	ds_read_b32 v47, v69 offset:12512
	ds_read_b32 v48, v69 offset:16608
	s_waitcnt vmcnt(15)
	s_waitcnt lgkmcnt(0)
	v_fmac_f32_e32 v144, v136, v44
	v_fmac_f32_e32 v145, v137, v44
	v_fmac_f32_e32 v146, v138, v44
	v_fmac_f32_e32 v147, v139, v44
	v_fmac_f32_e32 v148, v136, v45
	v_fmac_f32_e32 v149, v137, v45
	v_fmac_f32_e32 v150, v138, v45
	v_fmac_f32_e32 v151, v139, v45
	v_fmac_f32_e32 v152, v136, v46
	v_fmac_f32_e32 v153, v137, v46
	v_fmac_f32_e32 v154, v138, v46
	v_fmac_f32_e32 v155, v139, v46
	v_fmac_f32_e32 v156, v136, v47
	v_fmac_f32_e32 v157, v137, v47
	v_fmac_f32_e32 v158, v138, v47
	v_fmac_f32_e32 v159, v139, v47
	v_fmac_f32_e32 v160, v136, v48
	v_fmac_f32_e32 v161, v137, v48
	v_fmac_f32_e32 v162, v138, v48
	v_fmac_f32_e32 v163, v139, v48
	global_load_dwordx4 v[136:139], v[76:77], off
	v_lshl_add_u64 v[76:77], v[76:77], 0, s[0:1]
	ds_read_b32 v44, v69 offset:240
	ds_read_b32 v45, v69 offset:4336
	ds_read_b32 v46, v69 offset:8432
	ds_read_b32 v47, v69 offset:12528
	ds_read_b32 v48, v69 offset:16624
	s_waitcnt vmcnt(15)
	s_waitcnt lgkmcnt(0)
	v_fmac_f32_e32 v144, v140, v44
	v_fmac_f32_e32 v145, v141, v44
	v_fmac_f32_e32 v146, v142, v44
	v_fmac_f32_e32 v147, v143, v44
	v_fmac_f32_e32 v148, v140, v45
	v_fmac_f32_e32 v149, v141, v45
	v_fmac_f32_e32 v150, v142, v45
	v_fmac_f32_e32 v151, v143, v45
	v_fmac_f32_e32 v152, v140, v46
	v_fmac_f32_e32 v153, v141, v46
	v_fmac_f32_e32 v154, v142, v46
	v_fmac_f32_e32 v155, v143, v46
	v_fmac_f32_e32 v156, v140, v47
	v_fmac_f32_e32 v157, v141, v47
	v_fmac_f32_e32 v158, v142, v47
	v_fmac_f32_e32 v159, v143, v47
	v_fmac_f32_e32 v160, v140, v48
	v_fmac_f32_e32 v161, v141, v48
	v_fmac_f32_e32 v162, v142, v48
	v_fmac_f32_e32 v163, v143, v48
	global_load_dwordx4 v[140:143], v[76:77], off
	v_lshl_add_u64 v[76:77], v[76:77], 0, s[0:1]
	ds_read_b32 v44, v69 offset:256
	ds_read_b32 v45, v69 offset:4352
	ds_read_b32 v46, v69 offset:8448
	ds_read_b32 v47, v69 offset:12544
	ds_read_b32 v48, v69 offset:16640
	s_waitcnt vmcnt(15)
	s_waitcnt lgkmcnt(0)
	v_fmac_f32_e32 v144, v80, v44
	v_fmac_f32_e32 v145, v81, v44
	v_fmac_f32_e32 v146, v82, v44
	v_fmac_f32_e32 v147, v83, v44
	v_fmac_f32_e32 v148, v80, v45
	v_fmac_f32_e32 v149, v81, v45
	v_fmac_f32_e32 v150, v82, v45
	v_fmac_f32_e32 v151, v83, v45
	v_fmac_f32_e32 v152, v80, v46
	v_fmac_f32_e32 v153, v81, v46
	v_fmac_f32_e32 v154, v82, v46
	v_fmac_f32_e32 v155, v83, v46
	v_fmac_f32_e32 v156, v80, v47
	v_fmac_f32_e32 v157, v81, v47
	v_fmac_f32_e32 v158, v82, v47
	v_fmac_f32_e32 v159, v83, v47
	v_fmac_f32_e32 v160, v80, v48
	v_fmac_f32_e32 v161, v81, v48
	v_fmac_f32_e32 v162, v82, v48
	v_fmac_f32_e32 v163, v83, v48
	ds_read_b32 v44, v69 offset:272
	ds_read_b32 v45, v69 offset:4368
	ds_read_b32 v46, v69 offset:8464
	ds_read_b32 v47, v69 offset:12560
	ds_read_b32 v48, v69 offset:16656
	s_waitcnt vmcnt(14)
	s_waitcnt lgkmcnt(0)
	v_fmac_f32_e32 v144, v84, v44
	v_fmac_f32_e32 v145, v85, v44
	v_fmac_f32_e32 v146, v86, v44
	v_fmac_f32_e32 v147, v87, v44
	v_fmac_f32_e32 v148, v84, v45
	v_fmac_f32_e32 v149, v85, v45
	v_fmac_f32_e32 v150, v86, v45
	v_fmac_f32_e32 v151, v87, v45
	v_fmac_f32_e32 v152, v84, v46
	v_fmac_f32_e32 v153, v85, v46
	v_fmac_f32_e32 v154, v86, v46
	v_fmac_f32_e32 v155, v87, v46
	v_fmac_f32_e32 v156, v84, v47
	v_fmac_f32_e32 v157, v85, v47
	v_fmac_f32_e32 v158, v86, v47
	v_fmac_f32_e32 v159, v87, v47
	v_fmac_f32_e32 v160, v84, v48
	v_fmac_f32_e32 v161, v85, v48
	v_fmac_f32_e32 v162, v86, v48
	v_fmac_f32_e32 v163, v87, v48
	ds_read_b32 v44, v69 offset:288
	ds_read_b32 v45, v69 offset:4384
	ds_read_b32 v46, v69 offset:8480
	ds_read_b32 v47, v69 offset:12576
	ds_read_b32 v48, v69 offset:16672
	s_waitcnt vmcnt(13)
	s_waitcnt lgkmcnt(0)
	v_fmac_f32_e32 v144, v88, v44
	v_fmac_f32_e32 v145, v89, v44
	v_fmac_f32_e32 v146, v90, v44
	v_fmac_f32_e32 v147, v91, v44
	v_fmac_f32_e32 v148, v88, v45
	v_fmac_f32_e32 v149, v89, v45
	v_fmac_f32_e32 v150, v90, v45
	v_fmac_f32_e32 v151, v91, v45
	v_fmac_f32_e32 v152, v88, v46
	v_fmac_f32_e32 v153, v89, v46
	v_fmac_f32_e32 v154, v90, v46
	v_fmac_f32_e32 v155, v91, v46
	v_fmac_f32_e32 v156, v88, v47
	v_fmac_f32_e32 v157, v89, v47
	v_fmac_f32_e32 v158, v90, v47
	v_fmac_f32_e32 v159, v91, v47
	v_fmac_f32_e32 v160, v88, v48
	v_fmac_f32_e32 v161, v89, v48
	v_fmac_f32_e32 v162, v90, v48
	v_fmac_f32_e32 v163, v91, v48
	ds_read_b32 v44, v69 offset:304
	ds_read_b32 v45, v69 offset:4400
	ds_read_b32 v46, v69 offset:8496
	ds_read_b32 v47, v69 offset:12592
	ds_read_b32 v48, v69 offset:16688
	s_waitcnt vmcnt(12)
	s_waitcnt lgkmcnt(0)
	v_fmac_f32_e32 v144, v92, v44
	v_fmac_f32_e32 v145, v93, v44
	v_fmac_f32_e32 v146, v94, v44
	v_fmac_f32_e32 v147, v95, v44
	v_fmac_f32_e32 v148, v92, v45
	v_fmac_f32_e32 v149, v93, v45
	v_fmac_f32_e32 v150, v94, v45
	v_fmac_f32_e32 v151, v95, v45
	v_fmac_f32_e32 v152, v92, v46
	v_fmac_f32_e32 v153, v93, v46
	v_fmac_f32_e32 v154, v94, v46
	v_fmac_f32_e32 v155, v95, v46
	v_fmac_f32_e32 v156, v92, v47
	v_fmac_f32_e32 v157, v93, v47
	v_fmac_f32_e32 v158, v94, v47
	v_fmac_f32_e32 v159, v95, v47
	v_fmac_f32_e32 v160, v92, v48
	v_fmac_f32_e32 v161, v93, v48
	v_fmac_f32_e32 v162, v94, v48
	v_fmac_f32_e32 v163, v95, v48
	ds_read_b32 v44, v69 offset:320
	ds_read_b32 v45, v69 offset:4416
	ds_read_b32 v46, v69 offset:8512
	ds_read_b32 v47, v69 offset:12608
	ds_read_b32 v48, v69 offset:16704
	s_waitcnt vmcnt(11)
	s_waitcnt lgkmcnt(0)
	v_fmac_f32_e32 v144, v96, v44
	v_fmac_f32_e32 v145, v97, v44
	v_fmac_f32_e32 v146, v98, v44
	v_fmac_f32_e32 v147, v99, v44
	v_fmac_f32_e32 v148, v96, v45
	v_fmac_f32_e32 v149, v97, v45
	v_fmac_f32_e32 v150, v98, v45
	v_fmac_f32_e32 v151, v99, v45
	v_fmac_f32_e32 v152, v96, v46
	v_fmac_f32_e32 v153, v97, v46
	v_fmac_f32_e32 v154, v98, v46
	v_fmac_f32_e32 v155, v99, v46
	v_fmac_f32_e32 v156, v96, v47
	v_fmac_f32_e32 v157, v97, v47
	v_fmac_f32_e32 v158, v98, v47
	v_fmac_f32_e32 v159, v99, v47
	v_fmac_f32_e32 v160, v96, v48
	v_fmac_f32_e32 v161, v97, v48
	v_fmac_f32_e32 v162, v98, v48
	v_fmac_f32_e32 v163, v99, v48
	ds_read_b32 v44, v69 offset:336
	ds_read_b32 v45, v69 offset:4432
	ds_read_b32 v46, v69 offset:8528
	ds_read_b32 v47, v69 offset:12624
	ds_read_b32 v48, v69 offset:16720
	s_waitcnt vmcnt(10)
	s_waitcnt lgkmcnt(0)
	v_fmac_f32_e32 v144, v100, v44
	v_fmac_f32_e32 v145, v101, v44
	v_fmac_f32_e32 v146, v102, v44
	v_fmac_f32_e32 v147, v103, v44
	v_fmac_f32_e32 v148, v100, v45
	v_fmac_f32_e32 v149, v101, v45
	v_fmac_f32_e32 v150, v102, v45
	v_fmac_f32_e32 v151, v103, v45
	v_fmac_f32_e32 v152, v100, v46
	v_fmac_f32_e32 v153, v101, v46
	v_fmac_f32_e32 v154, v102, v46
	v_fmac_f32_e32 v155, v103, v46
	v_fmac_f32_e32 v156, v100, v47
	v_fmac_f32_e32 v157, v101, v47
	v_fmac_f32_e32 v158, v102, v47
	v_fmac_f32_e32 v159, v103, v47
	v_fmac_f32_e32 v160, v100, v48
	v_fmac_f32_e32 v161, v101, v48
	v_fmac_f32_e32 v162, v102, v48
	v_fmac_f32_e32 v163, v103, v48
	ds_read_b32 v44, v69 offset:352
	ds_read_b32 v45, v69 offset:4448
	ds_read_b32 v46, v69 offset:8544
	ds_read_b32 v47, v69 offset:12640
	ds_read_b32 v48, v69 offset:16736
	s_waitcnt vmcnt(9)
	s_waitcnt lgkmcnt(0)
	v_fmac_f32_e32 v144, v104, v44
	v_fmac_f32_e32 v145, v105, v44
	v_fmac_f32_e32 v146, v106, v44
	v_fmac_f32_e32 v147, v107, v44
	v_fmac_f32_e32 v148, v104, v45
	v_fmac_f32_e32 v149, v105, v45
	v_fmac_f32_e32 v150, v106, v45
	v_fmac_f32_e32 v151, v107, v45
	v_fmac_f32_e32 v152, v104, v46
	v_fmac_f32_e32 v153, v105, v46
	v_fmac_f32_e32 v154, v106, v46
	v_fmac_f32_e32 v155, v107, v46
	v_fmac_f32_e32 v156, v104, v47
	v_fmac_f32_e32 v157, v105, v47
	v_fmac_f32_e32 v158, v106, v47
	v_fmac_f32_e32 v159, v107, v47
	v_fmac_f32_e32 v160, v104, v48
	v_fmac_f32_e32 v161, v105, v48
	v_fmac_f32_e32 v162, v106, v48
	v_fmac_f32_e32 v163, v107, v48
	ds_read_b32 v44, v69 offset:368
	ds_read_b32 v45, v69 offset:4464
	ds_read_b32 v46, v69 offset:8560
	ds_read_b32 v47, v69 offset:12656
	ds_read_b32 v48, v69 offset:16752
	s_waitcnt vmcnt(8)
	s_waitcnt lgkmcnt(0)
	v_fmac_f32_e32 v144, v108, v44
	v_fmac_f32_e32 v145, v109, v44
	v_fmac_f32_e32 v146, v110, v44
	v_fmac_f32_e32 v147, v111, v44
	v_fmac_f32_e32 v148, v108, v45
	v_fmac_f32_e32 v149, v109, v45
	v_fmac_f32_e32 v150, v110, v45
	v_fmac_f32_e32 v151, v111, v45
	v_fmac_f32_e32 v152, v108, v46
	v_fmac_f32_e32 v153, v109, v46
	v_fmac_f32_e32 v154, v110, v46
	v_fmac_f32_e32 v155, v111, v46
	v_fmac_f32_e32 v156, v108, v47
	v_fmac_f32_e32 v157, v109, v47
	v_fmac_f32_e32 v158, v110, v47
	v_fmac_f32_e32 v159, v111, v47
	v_fmac_f32_e32 v160, v108, v48
	v_fmac_f32_e32 v161, v109, v48
	v_fmac_f32_e32 v162, v110, v48
	v_fmac_f32_e32 v163, v111, v48
	ds_read_b32 v44, v69 offset:384
	ds_read_b32 v45, v69 offset:4480
	ds_read_b32 v46, v69 offset:8576
	ds_read_b32 v47, v69 offset:12672
	ds_read_b32 v48, v69 offset:16768
	s_waitcnt vmcnt(7)
	s_waitcnt lgkmcnt(0)
	v_fmac_f32_e32 v144, v112, v44
	v_fmac_f32_e32 v145, v113, v44
	v_fmac_f32_e32 v146, v114, v44
	v_fmac_f32_e32 v147, v115, v44
	v_fmac_f32_e32 v148, v112, v45
	v_fmac_f32_e32 v149, v113, v45
	v_fmac_f32_e32 v150, v114, v45
	v_fmac_f32_e32 v151, v115, v45
	v_fmac_f32_e32 v152, v112, v46
	v_fmac_f32_e32 v153, v113, v46
	v_fmac_f32_e32 v154, v114, v46
	v_fmac_f32_e32 v155, v115, v46
	v_fmac_f32_e32 v156, v112, v47
	v_fmac_f32_e32 v157, v113, v47
	v_fmac_f32_e32 v158, v114, v47
	v_fmac_f32_e32 v159, v115, v47
	v_fmac_f32_e32 v160, v112, v48
	v_fmac_f32_e32 v161, v113, v48
	v_fmac_f32_e32 v162, v114, v48
	v_fmac_f32_e32 v163, v115, v48
	ds_read_b32 v44, v69 offset:400
	ds_read_b32 v45, v69 offset:4496
	ds_read_b32 v46, v69 offset:8592
	ds_read_b32 v47, v69 offset:12688
	ds_read_b32 v48, v69 offset:16784
	s_waitcnt vmcnt(6)
	s_waitcnt lgkmcnt(0)
	v_fmac_f32_e32 v144, v116, v44
	v_fmac_f32_e32 v145, v117, v44
	v_fmac_f32_e32 v146, v118, v44
	v_fmac_f32_e32 v147, v119, v44
	v_fmac_f32_e32 v148, v116, v45
	v_fmac_f32_e32 v149, v117, v45
	v_fmac_f32_e32 v150, v118, v45
	v_fmac_f32_e32 v151, v119, v45
	v_fmac_f32_e32 v152, v116, v46
	v_fmac_f32_e32 v153, v117, v46
	v_fmac_f32_e32 v154, v118, v46
	v_fmac_f32_e32 v155, v119, v46
	v_fmac_f32_e32 v156, v116, v47
	v_fmac_f32_e32 v157, v117, v47
	v_fmac_f32_e32 v158, v118, v47
	v_fmac_f32_e32 v159, v119, v47
	v_fmac_f32_e32 v160, v116, v48
	v_fmac_f32_e32 v161, v117, v48
	v_fmac_f32_e32 v162, v118, v48
	v_fmac_f32_e32 v163, v119, v48
	ds_read_b32 v44, v69 offset:416
	ds_read_b32 v45, v69 offset:4512
	ds_read_b32 v46, v69 offset:8608
	ds_read_b32 v47, v69 offset:12704
	ds_read_b32 v48, v69 offset:16800
	s_waitcnt vmcnt(5)
	s_waitcnt lgkmcnt(0)
	v_fmac_f32_e32 v144, v120, v44
	v_fmac_f32_e32 v145, v121, v44
	v_fmac_f32_e32 v146, v122, v44
	v_fmac_f32_e32 v147, v123, v44
	v_fmac_f32_e32 v148, v120, v45
	v_fmac_f32_e32 v149, v121, v45
	v_fmac_f32_e32 v150, v122, v45
	v_fmac_f32_e32 v151, v123, v45
	v_fmac_f32_e32 v152, v120, v46
	v_fmac_f32_e32 v153, v121, v46
	v_fmac_f32_e32 v154, v122, v46
	v_fmac_f32_e32 v155, v123, v46
	v_fmac_f32_e32 v156, v120, v47
	v_fmac_f32_e32 v157, v121, v47
	v_fmac_f32_e32 v158, v122, v47
	v_fmac_f32_e32 v159, v123, v47
	v_fmac_f32_e32 v160, v120, v48
	v_fmac_f32_e32 v161, v121, v48
	v_fmac_f32_e32 v162, v122, v48
	v_fmac_f32_e32 v163, v123, v48
	ds_read_b32 v44, v69 offset:432
	ds_read_b32 v45, v69 offset:4528
	ds_read_b32 v46, v69 offset:8624
	ds_read_b32 v47, v69 offset:12720
	ds_read_b32 v48, v69 offset:16816
	s_waitcnt vmcnt(4)
	s_waitcnt lgkmcnt(0)
	v_fmac_f32_e32 v144, v124, v44
	v_fmac_f32_e32 v145, v125, v44
	v_fmac_f32_e32 v146, v126, v44
	v_fmac_f32_e32 v147, v127, v44
	v_fmac_f32_e32 v148, v124, v45
	v_fmac_f32_e32 v149, v125, v45
	v_fmac_f32_e32 v150, v126, v45
	v_fmac_f32_e32 v151, v127, v45
	v_fmac_f32_e32 v152, v124, v46
	v_fmac_f32_e32 v153, v125, v46
	v_fmac_f32_e32 v154, v126, v46
	v_fmac_f32_e32 v155, v127, v46
	v_fmac_f32_e32 v156, v124, v47
	v_fmac_f32_e32 v157, v125, v47
	v_fmac_f32_e32 v158, v126, v47
	v_fmac_f32_e32 v159, v127, v47
	v_fmac_f32_e32 v160, v124, v48
	v_fmac_f32_e32 v161, v125, v48
	v_fmac_f32_e32 v162, v126, v48
	v_fmac_f32_e32 v163, v127, v48
	ds_read_b32 v44, v69 offset:448
	ds_read_b32 v45, v69 offset:4544
	ds_read_b32 v46, v69 offset:8640
	ds_read_b32 v47, v69 offset:12736
	ds_read_b32 v48, v69 offset:16832
	s_waitcnt vmcnt(3)
	s_waitcnt lgkmcnt(0)
	v_fmac_f32_e32 v144, v128, v44
	v_fmac_f32_e32 v145, v129, v44
	v_fmac_f32_e32 v146, v130, v44
	v_fmac_f32_e32 v147, v131, v44
	v_fmac_f32_e32 v148, v128, v45
	v_fmac_f32_e32 v149, v129, v45
	v_fmac_f32_e32 v150, v130, v45
	v_fmac_f32_e32 v151, v131, v45
	v_fmac_f32_e32 v152, v128, v46
	v_fmac_f32_e32 v153, v129, v46
	v_fmac_f32_e32 v154, v130, v46
	v_fmac_f32_e32 v155, v131, v46
	v_fmac_f32_e32 v156, v128, v47
	v_fmac_f32_e32 v157, v129, v47
	v_fmac_f32_e32 v158, v130, v47
	v_fmac_f32_e32 v159, v131, v47
	v_fmac_f32_e32 v160, v128, v48
	v_fmac_f32_e32 v161, v129, v48
	v_fmac_f32_e32 v162, v130, v48
	v_fmac_f32_e32 v163, v131, v48
	ds_read_b32 v44, v69 offset:464
	ds_read_b32 v45, v69 offset:4560
	ds_read_b32 v46, v69 offset:8656
	ds_read_b32 v47, v69 offset:12752
	ds_read_b32 v48, v69 offset:16848
	s_waitcnt vmcnt(2)
	s_waitcnt lgkmcnt(0)
	v_fmac_f32_e32 v144, v132, v44
	v_fmac_f32_e32 v145, v133, v44
	v_fmac_f32_e32 v146, v134, v44
	v_fmac_f32_e32 v147, v135, v44
	v_fmac_f32_e32 v148, v132, v45
	v_fmac_f32_e32 v149, v133, v45
	v_fmac_f32_e32 v150, v134, v45
	v_fmac_f32_e32 v151, v135, v45
	v_fmac_f32_e32 v152, v132, v46
	v_fmac_f32_e32 v153, v133, v46
	v_fmac_f32_e32 v154, v134, v46
	v_fmac_f32_e32 v155, v135, v46
	v_fmac_f32_e32 v156, v132, v47
	v_fmac_f32_e32 v157, v133, v47
	v_fmac_f32_e32 v158, v134, v47
	v_fmac_f32_e32 v159, v135, v47
	v_fmac_f32_e32 v160, v132, v48
	v_fmac_f32_e32 v161, v133, v48
	v_fmac_f32_e32 v162, v134, v48
	v_fmac_f32_e32 v163, v135, v48
	ds_read_b32 v44, v69 offset:480
	ds_read_b32 v45, v69 offset:4576
	ds_read_b32 v46, v69 offset:8672
	ds_read_b32 v47, v69 offset:12768
	ds_read_b32 v48, v69 offset:16864
	s_waitcnt vmcnt(1)
	s_waitcnt lgkmcnt(0)
	v_fmac_f32_e32 v144, v136, v44
	v_fmac_f32_e32 v145, v137, v44
	v_fmac_f32_e32 v146, v138, v44
	v_fmac_f32_e32 v147, v139, v44
	v_fmac_f32_e32 v148, v136, v45
	v_fmac_f32_e32 v149, v137, v45
	v_fmac_f32_e32 v150, v138, v45
	v_fmac_f32_e32 v151, v139, v45
	v_fmac_f32_e32 v152, v136, v46
	v_fmac_f32_e32 v153, v137, v46
	v_fmac_f32_e32 v154, v138, v46
	v_fmac_f32_e32 v155, v139, v46
	v_fmac_f32_e32 v156, v136, v47
	v_fmac_f32_e32 v157, v137, v47
	v_fmac_f32_e32 v158, v138, v47
	v_fmac_f32_e32 v159, v139, v47
	v_fmac_f32_e32 v160, v136, v48
	v_fmac_f32_e32 v161, v137, v48
	v_fmac_f32_e32 v162, v138, v48
	v_fmac_f32_e32 v163, v139, v48
	ds_read_b32 v44, v69 offset:496
	ds_read_b32 v45, v69 offset:4592
	ds_read_b32 v46, v69 offset:8688
	ds_read_b32 v47, v69 offset:12784
	ds_read_b32 v48, v69 offset:16880
	s_waitcnt vmcnt(0)
	s_waitcnt lgkmcnt(0)
	v_fmac_f32_e32 v144, v140, v44
	v_fmac_f32_e32 v145, v141, v44
	v_fmac_f32_e32 v146, v142, v44
	v_fmac_f32_e32 v147, v143, v44
	v_fmac_f32_e32 v148, v140, v45
	v_fmac_f32_e32 v149, v141, v45
	v_fmac_f32_e32 v150, v142, v45
	v_fmac_f32_e32 v151, v143, v45
	v_fmac_f32_e32 v152, v140, v46
	v_fmac_f32_e32 v153, v141, v46
	v_fmac_f32_e32 v154, v142, v46
	v_fmac_f32_e32 v155, v143, v46
	v_fmac_f32_e32 v156, v140, v47
	v_fmac_f32_e32 v157, v141, v47
	v_fmac_f32_e32 v158, v142, v47
	v_fmac_f32_e32 v159, v143, v47
	v_fmac_f32_e32 v160, v140, v48
	v_fmac_f32_e32 v161, v141, v48
	v_fmac_f32_e32 v162, v142, v48
	v_fmac_f32_e32 v163, v143, v48
	v_lshrrev_b32_e32 v67, 6, v186
	v_mul_u32_u24_e32 v67, 0x1400, v67
	v_add_u32_e32 v67, 0x10000, v67
	v_lshl_add_u32 v70, v66, 6, v67
	v_lshl_add_u32 v70, v65, 2, v70
	v_lshl_add_u32 v71, v64, 4, v67
	ds_write_b32 v70, v144 offset:0
	ds_write_b32 v70, v145 offset:16
	ds_write_b32 v70, v146 offset:32
	ds_write_b32 v70, v147 offset:48
	ds_write_b32 v70, v148 offset:1024
	ds_write_b32 v70, v149 offset:1040
	ds_write_b32 v70, v150 offset:1056
	ds_write_b32 v70, v151 offset:1072
	ds_write_b32 v70, v152 offset:2048
	ds_write_b32 v70, v153 offset:2064
	ds_write_b32 v70, v154 offset:2080
	ds_write_b32 v70, v155 offset:2096
	ds_write_b32 v70, v156 offset:3072
	ds_write_b32 v70, v157 offset:3088
	ds_write_b32 v70, v158 offset:3104
	ds_write_b32 v70, v159 offset:3120
	ds_write_b32 v70, v160 offset:4096
	ds_write_b32 v70, v161 offset:4112
	ds_write_b32 v70, v162 offset:4128
	ds_write_b32 v70, v163 offset:4144
	s_waitcnt lgkmcnt(0)
	ds_read_b128 v[80:83], v71 offset:0
	ds_read_b128 v[84:87], v71 offset:1024
	ds_read_b128 v[88:91], v71 offset:2048
	ds_read_b128 v[92:95], v71 offset:3072
	ds_read_b128 v[96:99], v71 offset:4096
	s_waitcnt lgkmcnt(0)
	v_add_f32_e32 v80, v80, v81
	v_add_f32_e32 v82, v82, v83
	v_add_f32_e32 v22, v80, v82
	v_add_f32_e32 v84, v84, v85
	v_add_f32_e32 v86, v86, v87
	v_add_f32_e32 v23, v84, v86
	v_add_f32_e32 v88, v88, v89
	v_add_f32_e32 v90, v90, v91
	v_add_f32_e32 v4, v88, v90
	v_add_f32_e32 v92, v92, v93
	v_add_f32_e32 v94, v94, v95
	v_add_f32_e32 v25, v92, v94
	v_add_f32_e32 v96, v96, v97
	v_add_f32_e32 v98, v98, v99
	v_add_f32_e32 v24, v96, v98
	ds_write2st64_b32 v36, v22, v23 offset0:80 offset1:81
	ds_write2st64_b32 v36, v4, v25 offset0:82 offset1:83
	ds_write_b32 v36, v24 offset:21504
	s_waitcnt lgkmcnt(0)
	s_barrier
	s_and_saveexec_b64 s[0:1], s[4:5]
	s_cbranch_execz .LBB0_63
	s_mul_i32 s57, s52, 0xffffffa0
	s_add_i32 s57, s57, s2
	s_lshl_b32 s58, s57, 6
	s_add_i32 s56, s58, s56
	v_or_b32_e32 v20, s56, v0
	v_readlane_b32 s60, v247, 6
	v_ashrrev_i32_e32 v21, 31, v20
	v_readlane_b32 s70, v247, 16
	v_readlane_b32 s71, v247, 17
	v_mad_u64_u32 v[46:47], s[56:57], s52, 5, v[2:3]
	s_nop 0
	v_lshl_add_u64 v[20:21], v[20:21], 2, s[70:71]
	global_load_dword v4, v[20:21], off
	s_movk_i32 s52, 0x1800
	ds_read2st64_b32 v[20:21], v42 offset0:80 offset1:85
	ds_read2st64_b32 v[22:23], v42 offset0:90 offset1:95
	ds_read2st64_b32 v[24:25], v42 offset0:100 offset1:105
	ds_read2st64_b32 v[44:45], v42 offset0:110 offset1:115
	v_mul_lo_u32 v17, v46, s52
	v_add_u32_e32 v17, s58, v17
	v_or_b32_e32 v46, v17, v0
	s_waitcnt lgkmcnt(3)
	v_add_f32_e32 v17, 0, v20
	v_add_f32_e32 v17, v17, v21
	s_waitcnt lgkmcnt(2)
	v_add_f32_e32 v17, v17, v22
	v_add_f32_e32 v17, v17, v23
	s_waitcnt lgkmcnt(1)
	v_add_f32_e32 v17, v17, v24
	v_add_f32_e32 v17, v17, v25
	s_waitcnt lgkmcnt(0)
	v_add_f32_e32 v17, v17, v44
	v_readlane_b32 s56, v247, 0
	v_ashrrev_i32_e32 v47, 31, v46
	v_add_f32_e32 v17, v17, v45
	v_readlane_b32 s58, v247, 2
	v_readlane_b32 s59, v247, 3
	v_readlane_b32 s61, v247, 7
	v_readlane_b32 s62, v247, 8
	v_lshl_add_u64 v[20:21], v[46:47], 2, s[58:59]
	v_readlane_b32 s63, v247, 9
	v_readlane_b32 s64, v247, 10
	v_readlane_b32 s65, v247, 11
	v_readlane_b32 s66, v247, 12
	v_readlane_b32 s67, v247, 13
	v_readlane_b32 s68, v247, 14
	v_readlane_b32 s69, v247, 15
	v_readlane_b32 s72, v247, 18
	v_readlane_b32 s73, v247, 19
	v_readlane_b32 s74, v247, 20
	v_readlane_b32 s75, v247, 21
	v_readlane_b32 s57, v247, 1
	s_waitcnt vmcnt(0)
	v_add_f32_e32 v4, v17, v4
	global_store_dword v[20:21], v4, off
